# conv2d item loop step 2: consumers of the first six halo loads deferred (masks captured in VGPRs) so that all ~48 loads of an item are issued before the first wait
# baseline (speedup 1.0000x reference)
; __device__ __forceinline__ void conv2d_phase(const Frame& F, int l, bool with_ctx, bool dry) {
;     ...
;         const int ch = cc * 256 + lane * 4;
;         const float* wq = W9 + ch;
;         f32x4 w[9];
; #pragma unroll
;         for (int k = 0; k < 9; ++k) w[k] = *(const f32x4*)(wq + (size_t)k * FFN);
;         const f32x4 bias4 = *(const f32x4*)(Bc + ch);
;         const bf16_t* ubase = UV + (size_t)tok0 * NUP + ch;
;         u32x2 u[3][10];
; #pragma unroll
;         for (int dy = 0; dy < 3; ++dy) {
;             const bool rok = dy == 1 ? true : (dy == 0 ? up_ok : dn_ok);
; #pragma unroll
;             for (int j = 0; j < 10; ++j) {
;                 const int col = c0 - 1 + j; const bool ok = rok && col >= 0 && col < wlim;
;                 const unsigned msk = (unsigned)-(int)ok;
;                 const long off = (long)(((dy - 1) * GRIDW + (j - 1)) & (int)msk) * NUP;
;                 const u32x2 t = *(const u32x2*)(ubase + off);
;                 u[dy][j] = (u32x2){t.x & msk, t.y & msk};
;             }
;         }
.LBB0_2037:
	s_add_i32 s4, s6, -1
	s_or_b32 s5, s6, 1
	s_or_b32 s8, s6, 2
	s_or_b32 s9, s6, 3
	s_or_b32 s10, s6, 4
	s_or_b32 s11, s6, 5
	s_or_b32 s17, s6, 6
	s_or_b32 s28, s6, 7
	s_add_i32 s16, s6, 8
	s_cmp_lt_u32 s4, s7
	s_cselect_b64 s[0:1], -1, 0
	s_and_b64 s[0:1], s[0:1], exec
	s_cselect_b32 s75, -1, 0
	s_cmp_lt_u32 s16, s7
	s_cselect_b64 s[38:39], -1, 0
	s_and_b64 s[0:1], s[38:39], exec
	s_cselect_b32 s16, 0x16000, 0
	s_cmp_lt_u32 s28, s7
	s_cselect_b64 s[40:41], -1, 0
	s_and_b64 s[0:1], s[40:41], exec
	s_cselect_b32 s92, 0x13400, 0
	s_cmp_lt_u32 s17, s7
	s_cselect_b64 s[42:43], -1, 0
	s_and_b64 s[0:1], s[42:43], exec
	s_cselect_b32 s68, 0x10800, 0
	s_cmp_lt_u32 s11, s7
	s_cselect_b64 s[44:45], -1, 0
	s_and_b64 s[0:1], s[44:45], exec
	s_cselect_b32 s66, 0xdc00, 0
	s_cmp_lt_u32 s10, s7
	s_cselect_b64 s[76:77], -1, 0
	s_and_b64 s[0:1], s[76:77], exec
	s_cselect_b32 s10, 0xb000, 0
	s_cmp_lt_u32 s9, s7
	s_cselect_b64 s[82:83], -1, 0
	s_and_b64 s[0:1], s[82:83], exec
	s_cselect_b32 s62, 0x8400, 0
	s_cmp_lt_u32 s8, s7
	s_cselect_b64 s[64:65], -1, 0
	s_and_b64 s[0:1], s[64:65], exec
	s_cselect_b32 s88, 0x5800, 0
	s_cmp_lt_u32 s5, s7
	s_cselect_b64 vcc, -1, 0
	s_and_b64 s[0:1], vcc, exec
	s_cselect_b32 s28, 0x2c00, 0
	s_cmp_lt_u32 s4, s7
	s_cselect_b64 s[0:1], -1, 0
	s_mul_i32 s3, s3, 11
	s_and_b64 s[4:5], s[0:1], exec
	s_cselect_b32 s74, 0xffffd400, 0
	s_sub_i32 s2, s2, s3
	v_lshl_add_u32 v42, s2, 8, v0
	v_ashrrev_i32_e32 v43, 31, v42
	v_readlane_b32 s2, v255, 21
	v_lshlrev_b64 v[38:39], 2, v[42:43]
	v_readlane_b32 s3, v255, 22
	v_readlane_b32 s4, v254, 19
	v_readlane_b32 s5, v254, 20
	s_waitcnt lgkmcnt(0)
	v_lshl_add_u64 v[2:3], s[2:3], 0, v[38:39]
	s_movk_i32 s2, 0x2000
	v_add_co_u32_e64 v4, s[2:3], s2, v2
	s_mov_b32 s11, s29
	s_nop 0
	v_addc_co_u32_e64 v5, s[2:3], 0, v3, s[2:3]
	s_movk_i32 s2, 0x5000
	s_nop 0
	v_add_co_u32_e64 v6, s[2:3], s2, v2
	s_mov_b32 s89, s29
	s_nop 0
	v_addc_co_u32_e64 v7, s[2:3], 0, v3, s[2:3]
	s_mov_b32 s2, 0x8000
	s_nop 0
	v_add_co_u32_e64 v8, s[2:3], s2, v2
	s_mov_b32 s63, s29
	s_nop 0
	v_addc_co_u32_e64 v9, s[2:3], 0, v3, s[2:3]
	s_mov_b32 s2, 0xb000
	s_nop 0
	v_add_co_u32_e64 v10, s[2:3], s2, v2
	s_mov_b32 s67, s29
	s_nop 0
	v_addc_co_u32_e64 v11, s[2:3], 0, v3, s[2:3]
	s_mov_b32 s2, 0xd000
	s_nop 0
	v_add_co_u32_e64 v12, s[2:3], s2, v2
	s_mov_b32 s69, s29
	s_nop 0
	v_addc_co_u32_e64 v13, s[2:3], 0, v3, s[2:3]
	s_mov_b32 s2, 0x10000
	s_nop 0
	v_add_co_u32_e64 v14, s[2:3], s2, v2
	s_mov_b32 s93, s29
	s_nop 0
	v_addc_co_u32_e64 v15, s[2:3], 0, v3, s[2:3]
	s_mov_b32 s2, 0x13000
	s_nop 0
	v_add_co_u32_e64 v40, s[2:3], s2, v2
	s_mov_b32 s17, s29
	s_nop 0
	v_addc_co_u32_e64 v41, s[2:3], 0, v3, s[2:3]
	s_mov_b32 s2, 0x16000
	s_nop 0
	v_add_co_u32_e64 v44, s[2:3], s2, v2
	s_mov_b32 s36, 0x3f07dc22
	s_nop 0
	v_addc_co_u32_e64 v45, s[2:3], 0, v3, s[2:3]
	s_mul_i32 s2, s27, 0x2c00
	s_mul_hi_i32 s3, s27, 0x2c00
	s_add_u32 s2, s4, s2
	s_addc_u32 s3, s5, s3
	s_and_b64 s[4:5], s[70:71], s[0:1]
	v_lshl_add_u64 v[68:69], v[42:43], 1, s[2:3]
	s_and_b64 s[2:3], s[4:5], exec
	s_cselect_b32 s3, -1, 0
	s_cselect_b32 s2, 0xfff4d400, 0
	v_lshl_add_u64 v[164:165], v[68:69], 0, s[2:3]
	global_load_dwordx2 v[164:165], v[164:165], off
	s_cmp_lt_u32 s6, s7
	s_cselect_b64 s[2:3], -1, 0
	s_and_b64 s[6:7], s[70:71], s[2:3]
	s_and_b64 s[8:9], s[6:7], exec
	s_cselect_b32 s9, -1, 0
	s_cselect_b32 s8, 0xfff50000, 0
	v_lshl_add_u64 v[18:19], v[68:69], 0, s[8:9]
	s_and_b64 s[8:9], s[70:71], vcc
	s_and_b64 s[72:73], s[8:9], exec
	s_cselect_b32 s73, -1, 0
	s_cselect_b32 s72, 0xfff52c00, 0
	v_lshl_add_u64 v[20:21], v[68:69], 0, s[72:73]
	s_and_b64 s[46:47], s[70:71], s[64:65]
	s_and_b64 s[72:73], s[46:47], exec
	s_cselect_b32 s73, -1, 0
	s_cselect_b32 s72, 0xfff55800, 0
	v_lshl_add_u64 v[46:47], v[68:69], 0, s[72:73]
	v_lshl_add_u64 v[70:71], v[68:69], 0, s[10:11]
	v_lshl_add_u64 v[62:63], v[68:69], 0, s[88:89]
	v_lshl_add_u64 v[64:65], v[68:69], 0, s[62:63]
	s_mov_b64 s[50:51], s[46:47]
	s_mov_b32 s46, 0xbf38aa3b
	s_mov_b64 s[88:89], s[44:45]
	global_load_dwordx2 v[150:151], v[18:19], off
	global_load_dwordx2 v[152:153], v[20:21], off
	v_lshl_add_u64 v[154:155], v[68:69], 0, s[74:75]
	v_lshl_add_u64 v[162:163], v[68:69], 0, s[28:29]
	global_load_dwordx2 v[156:157], v[154:155], off
	global_load_dwordx2 v[158:159], v[68:69], off
	global_load_dwordx2 v[160:161], v[162:163], off
	v_mov_b32_e32 v166, s4
	v_mov_b32_e32 v167, s6
	v_mov_b32_e32 v168, s8
	s_and_b64 s[8:9], s[70:71], s[82:83]
	s_and_b64 s[4:5], s[8:9], exec
	s_cselect_b32 s5, -1, 0
	s_cselect_b32 s4, 0xfff58400, 0
	s_and_b64 s[6:7], s[70:71], s[76:77]
	v_lshl_add_u64 v[48:49], v[68:69], 0, s[4:5]
	s_and_b64 s[4:5], s[6:7], exec
	s_cselect_b32 s5, -1, 0
	s_cselect_b32 s4, 0xfff5b000, 0
	v_lshl_add_u64 v[50:51], v[68:69], 0, s[4:5]
	s_and_b64 s[4:5], s[70:71], s[44:45]
	v_writelane_b32 v255, s4, 27
	v_writelane_b32 v255, s5, 28
	s_and_b64 s[4:5], s[4:5], exec
	s_cselect_b32 s5, -1, 0
	s_cselect_b32 s4, 0xfff5dc00, 0
	v_lshl_add_u64 v[52:53], v[68:69], 0, s[4:5]
	s_and_b64 s[4:5], s[70:71], s[42:43]
	v_writelane_b32 v255, s4, 25
	s_mov_b64 s[74:75], s[42:43]
	v_mov_b32_e32 v169, s0
	v_writelane_b32 v255, s5, 26
	s_and_b64 s[4:5], s[4:5], exec
	s_cselect_b32 s5, -1, 0
	s_cselect_b32 s4, 0xfff60800, 0
	v_lshl_add_u64 v[54:55], v[68:69], 0, s[4:5]
	s_and_b64 s[4:5], s[70:71], s[40:41]
	v_writelane_b32 v255, s4, 23
	v_mov_b32_e32 v170, s2
	v_writelane_b32 v255, s5, 24
	s_and_b64 s[4:5], s[4:5], exec
	s_cselect_b32 s5, -1, 0
	s_cselect_b32 s4, 0xfff63400, 0
	s_and_b64 s[72:73], s[70:71], s[38:39]
	v_lshl_add_u64 v[56:57], v[68:69], 0, s[4:5]
	s_and_b64 s[4:5], s[72:73], exec
	s_cselect_b32 s5, -1, 0
; __device__ __forceinline__ void conv2d_phase(const Frame& F, int l, bool with_ctx, bool dry) {
;     ...
;         const int ch = cc * 256 + lane * 4;
;         const float* wq = W9 + ch;
;         f32x4 w[9];
; #pragma unroll
;         for (int k = 0; k < 9; ++k) w[k] = *(const f32x4*)(wq + (size_t)k * FFN);
;         const f32x4 bias4 = *(const f32x4*)(Bc + ch);
;         const bf16_t* ubase = UV + (size_t)tok0 * NUP + ch;
;         u32x2 u[3][10];
; #pragma unroll
;         for (int dy = 0; dy < 3; ++dy) {
;             const bool rok = dy == 1 ? true : (dy == 0 ? up_ok : dn_ok);
; #pragma unroll
;             for (int j = 0; j < 10; ++j) {
;                 const int col = c0 - 1 + j; const bool ok = rok && col >= 0 && col < wlim;
;                 const unsigned msk = (unsigned)-(int)ok;
;                 const long off = (long)(((dy - 1) * GRIDW + (j - 1)) & (int)msk) * NUP;
;                 const u32x2 t = *(const u32x2*)(ubase + off);
;                 u[dy][j] = (u32x2){t.x & msk, t.y & msk};
;             }
;         }
;         u32x2 vv[8];
; #pragma unroll
;         for (int t = 0; t < 8; ++t) vv[t] = *(const u32x2*)(ubase + (size_t)t * NUP + FFN);
	s_cselect_b32 s4, 0xfff66000, 0
	s_and_b64 s[0:1], s[30:31], s[0:1]
	v_lshl_add_u64 v[58:59], v[68:69], 0, s[4:5]
	s_and_b64 s[4:5], s[0:1], exec
	s_cselect_b32 s28, 0xad400, 0
	s_and_b64 s[2:3], s[30:31], s[2:3]
	s_and_b64 s[4:5], s[2:3], exec
	v_lshl_add_u64 v[16:17], v[68:69], 0, s[28:29]
	s_cselect_b32 s28, 0xb0000, 0
	global_load_dwordx2 v[72:73], v[16:17], off
	v_lshl_add_u64 v[16:17], v[68:69], 0, s[28:29]
	global_load_dwordx2 v[74:75], v[16:17], off
	v_mov_b32_e32 v171, vcc_lo
	s_and_b64 vcc, s[30:31], vcc
	s_and_b64 s[4:5], vcc, exec
	s_cselect_b32 s28, 0xb2c00, 0
	v_lshl_add_u64 v[16:17], v[68:69], 0, s[28:29]
	global_load_dwordx2 v[76:77], v[16:17], off
	global_load_dwordx4 v[34:37], v[2:3], off
	global_load_dwordx4 v[18:21], v[4:5], off offset:3072
	global_load_dwordx4 v[22:25], v[6:7], off offset:2048
	global_load_dwordx4 v[26:29], v[8:9], off offset:1024
	global_load_dwordx4 v[30:33], v[10:11], off
	s_nop 0
	global_load_dwordx4 v[10:13], v[12:13], off offset:3072
	s_nop 0
	global_load_dwordx4 v[14:17], v[14:15], off offset:2048
	s_nop 0
	global_load_dwordx4 v[2:5], v[40:41], off offset:1024
	global_load_dwordx4 v[6:9], v[44:45], off
	v_readlane_b32 s4, v255, 55
	v_readlane_b32 s5, v255, 56
	v_lshl_add_u64 v[38:39], s[4:5], 0, v[38:39]
	s_and_b64 s[4:5], s[30:31], s[64:65]
	global_load_dwordx4 v[38:41], v[38:39], off
	s_nop 0
	global_load_dwordx2 v[92:93], v[46:47], off
	global_load_dwordx2 v[80:81], v[48:49], off
	global_load_dwordx2 v[66:67], v[50:51], off
	global_load_dwordx2 v[60:61], v[52:53], off
	s_nop 0
	global_load_dwordx2 v[54:55], v[54:55], off
	s_nop 0
	global_load_dwordx2 v[48:49], v[56:57], off
	global_load_dwordx2 v[44:45], v[58:59], off
	global_load_dwordx2 v[94:95], v[62:63], off
	global_load_dwordx2 v[82:83], v[64:65], off
	s_nop 0
	global_load_dwordx2 v[70:71], v[70:71], off
	v_lshl_add_u64 v[46:47], v[68:69], 0, s[66:67]
	global_load_dwordx2 v[64:65], v[46:47], off
	s_mov_b64 s[66:67], s[38:39]
	s_mov_b64 s[70:71], s[40:41]
	s_waitcnt vmcnt(29)
	v_and_b32_e32 v109, v166, v164
	v_and_b32_e32 v108, v166, v165
	v_lshlrev_b32_e32 v110, 16, v109
	v_and_b32_e32 v111, 0xffff0000, v109
	s_waitcnt vmcnt(28)
	v_and_b32_e32 v107, v167, v150
	v_and_b32_e32 v106, v167, v151
	v_lshlrev_b32_e32 v116, 16, v107
	v_and_b32_e32 v117, 0xffff0000, v107
	v_lshlrev_b32_e32 v118, 16, v106
	v_and_b32_e32 v119, 0xffff0000, v106
	s_waitcnt vmcnt(27)
	v_and_b32_e32 v105, v168, v152
	v_and_b32_e32 v104, v168, v153
	v_lshlrev_b32_e32 v112, 16, v104
	v_and_b32_e32 v113, 0xffff0000, v104
	s_waitcnt vmcnt(26)
	v_and_b32_e32 v123, v169, v156
	v_and_b32_e32 v120, v169, v157
	s_waitcnt vmcnt(25)
	v_and_b32_e32 v121, v170, v158
	v_and_b32_e32 v122, v170, v159
	s_waitcnt vmcnt(24)
	v_and_b32_e32 v115, v171, v160
	v_and_b32_e32 v114, v171, v161
	v_lshlrev_b32_e32 v138, 16, v123
	v_and_b32_e32 v139, 0xffff0000, v123
	v_lshlrev_b32_e32 v140, 16, v120
	v_and_b32_e32 v141, 0xffff0000, v120
	v_lshlrev_b32_e32 v120, 16, v121
	v_and_b32_e32 v121, 0xffff0000, v121
	v_lshlrev_b32_e32 v104, 16, v115
	v_lshlrev_b32_e32 v124, 16, v122
	v_and_b32_e32 v125, 0xffff0000, v122
	v_lshlrev_b32_e32 v106, 16, v114
	v_and_b32_e32 v107, 0xffff0000, v114
	s_waitcnt vmcnt(23)
	v_cndmask_b32_e64 v133, 0, v72, s[0:1]
	v_cndmask_b32_e64 v132, 0, v73, s[0:1]
	s_and_b64 s[0:1], s[4:5], exec
	s_waitcnt vmcnt(22)
	v_cndmask_b32_e64 v126, 0, v74, s[2:3]
	v_cndmask_b32_e64 v127, 0, v75, s[2:3]
	s_cselect_b32 s28, 0xb5800, 0
	s_and_b64 s[2:3], s[30:31], s[82:83]
	s_and_b64 s[0:1], s[2:3], exec
	v_lshl_add_u64 v[50:51], v[68:69], 0, s[28:29]
	s_cselect_b32 s28, 0xb8400, 0
	s_and_b64 s[0:1], s[30:31], s[76:77]
	s_and_b64 s[10:11], s[0:1], exec
	global_load_dwordx2 v[100:101], v[50:51], off
	v_lshl_add_u64 v[50:51], v[68:69], 0, s[28:29]
	s_cselect_b32 s28, 0xbb000, 0
	s_and_b64 s[62:63], s[30:31], s[44:45]
	v_lshl_add_u64 v[46:47], v[68:69], 0, s[68:69]
	s_and_b64 s[10:11], s[62:63], exec
	global_load_dwordx2 v[58:59], v[46:47], off
	global_load_dwordx2 v[90:91], v[50:51], off
	v_lshl_add_u64 v[50:51], v[68:69], 0, s[28:29]
	s_cselect_b32 s28, 0xbdc00, 0
	s_and_b64 s[68:69], s[30:31], s[42:43]
	v_lshl_add_u64 v[46:47], v[68:69], 0, s[92:93]
	s_and_b64 s[10:11], s[68:69], exec
	global_load_dwordx2 v[52:53], v[46:47], off
	global_load_dwordx2 v[84:85], v[50:51], off
	v_lshl_add_u64 v[46:47], v[68:69], 0, s[16:17]
	v_lshl_add_u64 v[50:51], v[68:69], 0, s[28:29]
	s_cselect_b32 s28, 0xc0800, 0
	s_and_b64 s[16:17], s[30:31], s[40:41]
	s_and_b64 s[10:11], s[16:17], exec
	global_load_dwordx2 v[46:47], v[46:47], off
	s_waitcnt vmcnt(27)
	v_cndmask_b32_e32 v131, 0, v76, vcc
	global_load_dwordx2 v[72:73], v[50:51], off
	v_lshl_add_u64 v[50:51], v[68:69], 0, s[28:29]
	s_cselect_b32 s28, 0xc3400, 0
	s_and_b64 s[10:11], s[30:31], s[38:39]
	s_and_b64 s[30:31], s[10:11], exec
	global_load_dwordx2 v[62:63], v[50:51], off
	v_lshl_add_u64 v[50:51], v[68:69], 0, s[28:29]
	s_cselect_b32 s28, 0xc6000, 0
	global_load_dwordx2 v[56:57], v[50:51], off
	v_lshl_add_u64 v[50:51], v[68:69], 0, s[28:29]
	s_movk_i32 s28, 0x1000
	v_cndmask_b32_e32 v130, 0, v77, vcc
	v_add_co_u32_e32 v74, vcc, s28, v68
	s_movk_i32 s28, 0x4000
	s_nop 0
	v_addc_co_u32_e32 v75, vcc, 0, v69, vcc
	global_load_dwordx2 v[102:103], v[74:75], off offset:1536
	v_add_co_u32_e32 v74, vcc, s28, v68
	s_movk_i32 s28, 0x6000
	s_nop 0
	v_addc_co_u32_e32 v75, vcc, 0, v69, vcc
	global_load_dwordx2 v[50:51], v[50:51], off
	s_waitcnt vmcnt(22)
; __device__ __forceinline__ unsigned pk2(float lo, float hi) { const f32x2 v = {lo, hi}; const bf16x2_t b = __builtin_convertvector(v, bf16x2_t); return __builtin_bit_cast(unsigned, b); }
; __device__ __forceinline__ f32x2 gelu_pk(f32x2 v) {
;     const f32x2 av = __builtin_elementwise_abs(v), d = av * 0.2316418882f + 1.0f;
;     f32x2 t; t.x = __builtin_amdgcn_rcpf(d.x); t.y = __builtin_amdgcn_rcpf(d.y);
;     f32x2 q = t * 0.5307027145f + (-0.7265760135f); q = q * t + 0.7107068705f; q = q * t + (-0.142248368f); q = q * t + 0.127414796f; q = q * t;
;     const f32x2 s = (v * v) * (-0.72134752044f);
;     f32x2 e; e.x = __builtin_amdgcn_exp2f(s.x); e.y = __builtin_amdgcn_exp2f(s.y);
;     const f32x2 m = v * (q * e), r = v - m;
;     f32x2 o; o.x = v.x < 0.f ? m.x : r.x; o.y = v.y < 0.f ? m.y : r.y; return o;
; }
; __device__ __forceinline__ void conv2d_phase(const Frame& F, int l, bool with_ctx, bool dry) {
;     ...
; #pragma unroll
;         for (int t = 0; t < 8; ++t) {
;             f32x4 a = bias4;
; #pragma unroll
;             for (int dy = 0; dy < 3; ++dy)
; #pragma unroll
;                 for (int dx = 0; dx < 3; ++dx) {
;                     const u32x2 x = u[dy][t + dx]; const f32x4 ww = w[dy * 3 + dx];
;                     a.x += ww.x * bflo(x.x); a.y += ww.y * bfhi(x.x); a.z += ww.z * bflo(x.y); a.w += ww.w * bfhi(x.y);
;                 }
;             const f32x2 g0 = gelu_pk((f32x2){a.x, a.y}), g1 = gelu_pk((f32x2){a.z, a.w});
;             u32x2 o; o.x = pk2(g0.x * bflo(vv[t].x), g0.y * bfhi(vv[t].x)); o.y = pk2(g1.x * bflo(vv[t].y), g1.y * bfhi(vv[t].y));
;             bf16_t* vp = UV + (size_t)(tok0 + t) * NUP + FFN + ch;
;             if (!dry) *(u32x2*)vp = o; else asm volatile("" :: "v"(o));
	v_pk_fma_f32 v[134:135], v[34:35], v[110:111], v[38:39]
	global_load_dwordx2 v[96:97], v[74:75], off offset:512
	v_add_co_u32_e32 v74, vcc, s28, v68
	s_mov_b32 s28, 0x9000
	s_nop 0
	v_addc_co_u32_e32 v75, vcc, 0, v69, vcc
	global_load_dwordx2 v[98:99], v[74:75], off offset:3584
	v_add_co_u32_e32 v74, vcc, s28, v68
	s_mov_b32 s28, 0xc000
	s_nop 0
	v_addc_co_u32_e32 v75, vcc, 0, v69, vcc
	global_load_dwordx2 v[86:87], v[74:75], off offset:2560
	v_add_co_u32_e32 v74, vcc, s28, v68
	s_mov_b32 s28, 0xf000
	s_nop 0
	v_addc_co_u32_e32 v75, vcc, 0, v69, vcc
	global_load_dwordx2 v[76:77], v[74:75], off offset:1536
	v_add_co_u32_e32 v74, vcc, s28, v68
	s_mov_b32 s28, 0x11000
	s_nop 0
	v_addc_co_u32_e32 v75, vcc, 0, v69, vcc
	global_load_dwordx2 v[88:89], v[74:75], off offset:512
	v_add_co_u32_e32 v74, vcc, s28, v68
	s_mov_b32 s28, 0x14000
	s_nop 0
	v_addc_co_u32_e32 v75, vcc, 0, v69, vcc
	global_load_dwordx2 v[78:79], v[74:75], off offset:3584
	v_add_co_u32_e32 v74, vcc, s28, v68
	v_lshlrev_b32_e32 v110, 16, v108
	s_nop 0
	v_addc_co_u32_e32 v75, vcc, 0, v69, vcc
	global_load_dwordx2 v[74:75], v[74:75], off offset:2560
	v_and_b32_e32 v111, 0xffff0000, v108
	v_pk_fma_f32 v[136:137], v[36:37], v[110:111], v[40:41]
	v_lshlrev_b32_e32 v110, 16, v105
	v_and_b32_e32 v111, 0xffff0000, v105
	v_lshlrev_b32_e32 v142, 16, v133
	v_and_b32_e32 v143, 0xffff0000, v133
	v_lshlrev_b32_e32 v144, 16, v132
	v_and_b32_e32 v145, 0xffff0000, v132
	v_pk_fma_f32 v[132:133], v[18:19], v[116:117], v[134:135]
	v_and_b32_e32 v105, 0xffff0000, v115
	v_pk_fma_f32 v[132:133], v[22:23], v[110:111], v[132:133]
	v_lshlrev_b32_e32 v122, 16, v126
	v_pk_fma_f32 v[132:133], v[26:27], v[138:139], v[132:133]
	v_and_b32_e32 v123, 0xffff0000, v126
	v_pk_fma_f32 v[132:133], v[30:31], v[120:121], v[132:133]
	v_lshlrev_b32_e32 v108, 16, v131
	v_pk_fma_f32 v[132:133], v[10:11], v[104:105], v[132:133]
	v_and_b32_e32 v109, 0xffff0000, v131
	v_pk_fma_f32 v[132:133], v[14:15], v[142:143], v[132:133]
	s_mov_b32 s28, 0x3e6d3388
	v_pk_fma_f32 v[132:133], v[2:3], v[122:123], v[132:133]
	v_lshlrev_b32_e32 v114, 16, v130
	v_pk_fma_f32 v[132:133], v[6:7], v[108:109], v[132:133]
	v_and_b32_e32 v115, 0xffff0000, v130
	v_and_b32_e32 v135, 0x7fffffff, v133
	v_and_b32_e32 v134, 0x7fffffff, v132
	v_pk_fma_f32 v[134:135], v[134:135], s[28:29], 1.0 op_sel_hi:[1,0,0]
	v_pk_fma_f32 v[130:131], v[20:21], v[118:119], v[136:137]
	v_rcp_f32_e32 v134, v134
	v_rcp_f32_e32 v135, v135
	v_pk_fma_f32 v[130:131], v[24:25], v[112:113], v[130:131]
	s_mov_b32 s38, 0xbf3a00e3
	v_pk_fma_f32 v[130:131], v[28:29], v[140:141], v[130:131]
	v_mov_b64_e32 v[136:137], s[38:39]
	v_pk_mul_f32 v[140:141], v[132:133], v[132:133]
	v_pk_fma_f32 v[130:131], v[32:33], v[124:125], v[130:131]
	v_pk_fma_f32 v[138:139], v[134:135], s[36:37], v[136:137] op_sel_hi:[1,0,0]
	s_mov_b32 s40, 0x3f35f0e3
	v_pk_mul_f32 v[140:141], v[140:141], s[46:47] op_sel_hi:[1,0]
	v_pk_fma_f32 v[130:131], v[12:13], v[106:107], v[130:131]
	v_pk_fma_f32 v[138:139], v[134:135], v[138:139], s[40:41] op_sel_hi:[1,1,0]
	s_mov_b32 s42, 0xbe11a98e
	v_exp_f32_e32 v140, v140
	v_exp_f32_e32 v141, v141
	v_lshlrev_b32_e32 v126, 16, v127
	v_and_b32_e32 v127, 0xffff0000, v127
	v_pk_fma_f32 v[130:131], v[16:17], v[144:145], v[130:131]
	v_pk_fma_f32 v[138:139], v[134:135], v[138:139], s[42:43] op_sel_hi:[1,1,0]
	s_mov_b32 s44, 0x3e027906
	v_pk_fma_f32 v[130:131], v[4:5], v[126:127], v[130:131]
	v_pk_fma_f32 v[138:139], v[134:135], v[138:139], s[44:45] op_sel_hi:[1,1,0]
	v_pk_fma_f32 v[130:131], v[8:9], v[114:115], v[130:131]
	v_pk_mul_f32 v[134:135], v[134:135], v[138:139]
	v_cmp_gt_f32_e32 vcc, 0, v133
	v_pk_mul_f32 v[134:135], v[140:141], v[134:135]
	v_and_b32_e32 v141, 0x7fffffff, v131
	v_and_b32_e32 v140, 0x7fffffff, v130
	v_pk_fma_f32 v[140:141], v[140:141], s[28:29], 1.0 op_sel_hi:[1,0,0]
	v_pk_mul_f32 v[138:139], v[132:133], v[134:135]
	v_rcp_f32_e32 v140, v140
	v_rcp_f32_e32 v141, v141
	v_pk_fma_f32 v[134:135], v[132:133], v[134:135], v[132:133] neg_lo:[1,0,0] neg_hi:[1,0,0]
	s_mov_b64 s[30:31], -1
	v_cndmask_b32_e32 v133, v135, v139, vcc
	v_cmp_gt_f32_e32 vcc, 0, v132
	s_waitcnt vmcnt(8)
	v_and_b32_e32 v139, 0xffff0000, v102
	v_cndmask_b32_e32 v132, v134, v138, vcc
	v_pk_fma_f32 v[134:135], v[140:141], s[36:37], v[136:137] op_sel_hi:[1,0,0]
	v_pk_mul_f32 v[136:137], v[130:131], v[130:131]
	v_pk_fma_f32 v[134:135], v[140:141], v[134:135], s[40:41] op_sel_hi:[1,1,0]
	v_pk_mul_f32 v[136:137], v[136:137], s[46:47] op_sel_hi:[1,0]
	v_pk_fma_f32 v[134:135], v[140:141], v[134:135], s[42:43] op_sel_hi:[1,1,0]
	v_exp_f32_e32 v136, v136
	v_exp_f32_e32 v137, v137
	v_pk_fma_f32 v[134:135], v[140:141], v[134:135], s[44:45] op_sel_hi:[1,1,0]
	v_cmp_gt_f32_e32 vcc, 0, v131
	v_pk_mul_f32 v[134:135], v[140:141], v[134:135]
	v_lshlrev_b32_e32 v138, 16, v102
	v_pk_mul_f32 v[134:135], v[136:137], v[134:135]
	v_pk_mul_f32 v[132:133], v[132:133], v[138:139]
	v_pk_mul_f32 v[136:137], v[130:131], v[134:135]
	v_pk_fma_f32 v[134:135], v[130:131], v[134:135], v[130:131] neg_lo:[1,0,0] neg_hi:[1,0,0]
	v_cvt_pk_bf16_f32 v102, v132, v133
	v_cndmask_b32_e32 v131, v135, v137, vcc
	v_cmp_gt_f32_e32 vcc, 0, v130
	v_lshlrev_b32_e32 v132, 16, v103
	v_and_b32_e32 v133, 0xffff0000, v103
	v_cndmask_b32_e32 v130, v134, v136, vcc
	v_pk_mul_f32 v[130:131], v[130:131], v[132:133]
	s_and_b64 vcc, exec, s[48:49]
	v_cvt_pk_bf16_f32 v103, v130, v131
	s_cbranch_vccz .LBB0_2039
	s_mov_b64 s[30:31], 0
